# epilogue cache copy with system-scope streaming hints (sc0 sc1 nt) on its loads and stores
# baseline (speedup 1.0000x reference)
.LBB0_684:
	s_cmp_eq_u64 s[100:101], 0
	s_cbranch_scc1 .Lbg4_sskip
	v_readlane_b32 s98, v255, 62
	v_readlane_b32 s99, v255, 63
	s_add_u32 s98, s98, s100
	s_addc_u32 s99, s99, s101
	s_waitcnt vmcnt(8)
	v_mov_b32_e32 v2, v226
	v_mov_b32_e32 v3, v227
	v_lshlrev_b32_e32 v4, 21, v3
	v_lshl_add_u32 v4, v2, 4, v4
	v_mov_b32_e32 v5, 0
	v_lshl_add_u64 v[4:5], s[98:99], 0, v[4:5]
	v_cmp_gt_i32_e32 vcc, 64, v3
	s_nop 1
	s_mov_b64 exec, vcc
	s_nop 0
	global_store_dwordx4 v[4:5], v[236:239], off sc0 sc1 nt
	s_mov_b64 exec, -1
	v_subrev_u32_e32 v2, 64, v2
	v_subrev_u32_e32 v3, 1, v3
	v_cmp_gt_i32_e32 vcc, 0, v2
	v_add_u32_e32 v10, 0x1ffc0, v2
	s_nop 0
	v_cndmask_b32_e32 v2, v2, v10, vcc
	v_cndmask_b32_e64 v10, 0, 1, vcc
	v_sub_u32_e32 v3, v3, v10
	v_lshlrev_b32_e32 v6, 21, v3
	v_lshl_add_u32 v6, v2, 4, v6
	v_mov_b32_e32 v7, 0
	v_lshl_add_u64 v[6:7], s[98:99], 0, v[6:7]
	v_cmp_gt_i32_e32 vcc, 64, v3
	s_nop 1
	s_mov_b64 exec, vcc
	s_nop 0
	global_store_dwordx4 v[6:7], v[232:235], off sc0 sc1 nt
	s_mov_b64 exec, -1
	v_subrev_u32_e32 v2, 64, v2
	v_subrev_u32_e32 v3, 1, v3
	v_cmp_gt_i32_e32 vcc, 0, v2
	v_add_u32_e32 v10, 0x1ffc0, v2
	s_nop 0
	v_cndmask_b32_e32 v2, v2, v10, vcc
	v_cndmask_b32_e64 v10, 0, 1, vcc
	v_sub_u32_e32 v3, v3, v10
	v_lshlrev_b32_e32 v8, 21, v3
	v_lshl_add_u32 v8, v2, 4, v8
	v_mov_b32_e32 v9, 0
	v_lshl_add_u64 v[8:9], s[98:99], 0, v[8:9]
	v_cmp_gt_i32_e32 vcc, 64, v3
	s_nop 1
	s_mov_b64 exec, vcc
	s_nop 0
	global_store_dwordx4 v[8:9], v[228:231], off sc0 sc1 nt
	s_mov_b64 exec, -1

.LBB0_693:
	s_or_b64 exec, exec, s[18:19]
	s_cmp_eq_u64 s[100:101], 0
	s_cbranch_scc1 .Lbg4_lskip
	v_add_u32_e32 v226, 64, v226
	v_add_u32_e32 v227, 1, v227
	v_cmp_le_i32_e32 vcc, 0x1ffc0, v226
	v_subrev_u32_e32 v228, 0x1ffc0, v226
	s_nop 0
	v_cndmask_b32_e32 v226, v226, v228, vcc
	v_cndmask_b32_e64 v228, 0, 1, vcc
	v_add_u32_e32 v227, v227, v228
	v_lshlrev_b32_e32 v228, 21, v227
	v_lshl_add_u32 v228, v226, 4, v228
	v_mov_b32_e32 v229, 0
	v_lshl_add_u64 v[228:229], s[100:101], 0, v[228:229]
	v_cmp_gt_i32_e32 vcc, 64, v227
	s_nop 1
	s_mov_b64 exec, vcc
	s_nop 0
	global_load_dwordx4 v[228:231], v[228:229], off sc0 sc1 nt
	s_mov_b64 exec, -1
	v_add_u32_e32 v226, 64, v226
	v_add_u32_e32 v227, 1, v227
	v_cmp_le_i32_e32 vcc, 0x1ffc0, v226
	v_subrev_u32_e32 v232, 0x1ffc0, v226
	s_nop 0
	v_cndmask_b32_e32 v226, v226, v232, vcc
	v_cndmask_b32_e64 v232, 0, 1, vcc
	v_add_u32_e32 v227, v227, v232
	v_lshlrev_b32_e32 v232, 21, v227
	v_lshl_add_u32 v232, v226, 4, v232
	v_mov_b32_e32 v233, 0
	v_lshl_add_u64 v[232:233], s[100:101], 0, v[232:233]
	v_cmp_gt_i32_e32 vcc, 64, v227
	s_nop 1
	s_mov_b64 exec, vcc
	s_nop 0
	global_load_dwordx4 v[232:235], v[232:233], off sc0 sc1 nt
	s_mov_b64 exec, -1
	v_add_u32_e32 v226, 64, v226
	v_add_u32_e32 v227, 1, v227
	v_cmp_le_i32_e32 vcc, 0x1ffc0, v226
	v_subrev_u32_e32 v236, 0x1ffc0, v226
	s_nop 0
	v_cndmask_b32_e32 v226, v226, v236, vcc
	v_cndmask_b32_e64 v236, 0, 1, vcc
	v_add_u32_e32 v227, v227, v236
	v_lshlrev_b32_e32 v236, 21, v227
	v_lshl_add_u32 v236, v226, 4, v236
	v_mov_b32_e32 v237, 0
	v_lshl_add_u64 v[236:237], s[100:101], 0, v[236:237]
	v_cmp_gt_i32_e32 vcc, 64, v227
	s_nop 1
	s_mov_b64 exec, vcc
	s_nop 0
	global_load_dwordx4 v[236:239], v[236:237], off sc0 sc1 nt
	s_mov_b64 exec, -1
